# layer-1 w_in/w_glu weight conversion moved from the layer-0 GLU phase to the tile-less workgroups of the layer-0 w_up GEMM phase
# speedup vs baseline: 1.0093x; 1.0093x over previous
.LBB0_1652:
	s_cmp_gt_i32 s66, 4
	s_cselect_b64 s[0:1], -1, 0
	s_cmp_lt_i32 s67, 5
	s_cselect_b64 s[2:3], -1, 0
	s_or_b64 s[0:1], s[0:1], s[2:3]
	s_and_b64 vcc, exec, s[0:1]
	s_cbranch_vccnz .LBB0_1737
	s_mov_b32 s101, 0
	s_movk_i32 s100, 0x11ff
	s_cmpk_eq_i32 s64, 0x200
	s_cselect_b32 s100, 0xabf, s100
	s_lshr_b32 s3, s78, 3
	s_ashr_i32 s20, s64, 3
	v_readlane_b32 s36, v251, 23
	s_cmpk_gt_u32 s78, 0xff
	v_readlane_b32 s42, v251, 29
	v_readlane_b32 s43, v251, 30
	v_readlane_b32 s37, v251, 24
	v_readlane_b32 s38, v251, 25
	v_readlane_b32 s39, v251, 26
	v_readlane_b32 s40, v251, 27
	v_readlane_b32 s41, v251, 28
	v_readlane_b32 s44, v251, 31
	v_readlane_b32 s45, v251, 32
	v_readlane_b32 s46, v251, 33
	v_readlane_b32 s47, v251, 34
	v_readlane_b32 s48, v251, 35
	v_readlane_b32 s49, v251, 36
	v_readlane_b32 s50, v251, 37
	v_readlane_b32 s51, v251, 38
	s_cbranch_scc1 .LBB0_1662
	s_add_u32 s0, s30, 0xb793e00
	s_addc_u32 s1, s31, 0
	s_add_u32 s4, s30, 0x9393e00
	s_addc_u32 s5, s31, 0
	s_add_u32 s6, s30, 0x9b93e00
	s_addc_u32 s7, s31, 0
	s_add_u32 s8, s30, 0x1993e00
	s_addc_u32 s9, s31, 0
	s_add_u32 s10, s30, 0xa393e00
	s_addc_u32 s11, s31, 0
	s_lshl_b32 s2, s78, 10
	s_and_b32 s21, s2, 0x1c00
	s_lshl_b32 s22, s3, 7
	s_lshl_b32 s23, s20, 7
	s_lshl_b32 s24, s3, 4
	s_lshl_b32 s25, s20, 4
	s_add_u32 s14, s42, 0x100
	s_mov_b64 s[12:13], 0x100
	s_addc_u32 s15, s43, 0
	v_mov_b32_e32 v137, 0
	s_mov_b32 s26, 0x8000
	s_mov_b32 s27, 0x10000
	s_mov_b32 s33, 0x18000
	s_movk_i32 s34, 0x90
	s_mov_b32 s35, 0xfffffc0
	s_mov_b32 s40, s3
	s_branch .LBB0_1656

.LBB0_1662:
	s_and_b32 s0, s64, -8
	s_addk_i32 s0, 0xff00
	s_cmp_gt_i32 s20, 32
	s_cselect_b32 s2, s0, 0
	s_cmp_lg_u32 s2, 0
	s_cbranch_scc0 .LBB0_1664
	s_and_b32 s0, s78, 7
	s_sub_i32 s1, s20, 32
	s_mul_i32 s1, s1, s0
	s_add_i32 s3, s3, s1
	s_sub_i32 s0, s3, 32
	s_cmpk_gt_u32 s78, 0xff
	s_cselect_b32 s3, s0, 0x1200
	s_cmp_gt_i32 s3, s100
	s_cbranch_scc0 .LBB0_1665
	s_branch .LBB0_1687
.LBB0_1664:
	s_mov_b32 s2, s64
	s_mov_b32 s3, s78
	s_cmp_gt_i32 s3, s100
	s_cbranch_scc1 .LBB0_1687

.LBB0_1666:
	v_lshlrev_b32_e32 v0, 4, v4
	v_and_b32_e32 v4, 48, v0
	v_lshlrev_b32_e32 v0, 1, v4
	v_mul_u32_u24_e32 v4, 0x104, v4
	v_lshlrev_b32_e32 v5, 2, v5
	s_waitcnt vmcnt(10)
	v_add3_u32 v14, 32, v4, v5
	ds_read2_b32 v[4:5], v14 offset1:65
	ds_read2_b32 v[6:7], v14 offset0:130 offset1:195
	v_add_u32_e32 v10, 0x400, v14
	ds_read2_b32 v[8:9], v10 offset0:4 offset1:69
	ds_read2_b32 v[10:11], v10 offset0:134 offset1:199
	v_lshl_add_u64 v[12:13], v[2:3], 0, v[0:1]
	v_add_u32_e32 v0, 0x800, v14
	s_waitcnt lgkmcnt(3)
	v_cvt_pk_bf16_f32 v2, v4, v5
	s_waitcnt lgkmcnt(2)
	v_cvt_pk_bf16_f32 v3, v6, v7
	s_waitcnt lgkmcnt(1)
	v_cvt_pk_bf16_f32 v4, v8, v9
	ds_read2_b32 v[6:7], v0 offset0:8 offset1:73
	ds_read2_b32 v[8:9], v0 offset0:138 offset1:203
	v_add_u32_e32 v0, 0xc00, v14
	s_waitcnt lgkmcnt(2)
	v_cvt_pk_bf16_f32 v5, v10, v11
	ds_read2_b32 v[10:11], v0 offset0:12 offset1:77
	ds_read2_b32 v[14:15], v0 offset0:142 offset1:207
	s_add_i32 s3, s3, s2
	global_store_dwordx4 v[12:13], v[2:5], off
	s_cmp_gt_i32 s3, s100
	s_waitcnt lgkmcnt(3)
	v_cvt_pk_bf16_f32 v2, v6, v7
	s_waitcnt lgkmcnt(2)
	v_cvt_pk_bf16_f32 v3, v8, v9
	s_waitcnt lgkmcnt(1)
	v_cvt_pk_bf16_f32 v4, v10, v11
	s_waitcnt lgkmcnt(0)
	v_cvt_pk_bf16_f32 v5, v14, v15
	global_store_dwordx4 v[12:13], v[2:5], off offset:16
	s_cbranch_scc1 .LBB0_1687

.LBB0_1687:
	s_cmp_lg_u32 s101, 0
	s_cbranch_scc1 .Lcv_ret_p4
	s_cmp_gt_i32 s67, 5
	s_cbranch_scc0 .LBB0_1737
	s_waitcnt vmcnt(0)
	s_waitcnt vmcnt(63) expcnt(7) lgkmcnt(15)
	s_barrier
	s_mov_b64 s[4:5], exec
	v_readlane_b32 s2, v251, 3
	v_readlane_b32 s3, v251, 4
	s_and_b64 s[2:3], s[4:5], s[2:3]
	s_mov_b64 exec, s[2:3]
	s_cbranch_execz .Lxb_done_5
	v_mov_b32_e32 v0, 0
	s_waitcnt vmcnt(0) expcnt(0) lgkmcnt(0)
	ds_read_b32 v2, v0
	ds_read_b32 v1, v0 offset:4
	v_readlane_b32 s0, v251, 2
	v_readlane_b32 s6, v251, 5
	v_readlane_b32 s7, v251, 6
	s_lshl_b32 s0, s0, 8
	s_add_u32 s8, s6, s0
	s_addc_u32 s9, s7, 0
	v_mov_b32_e32 v3, 1
	v_mov_b32_e32 v4, 0x1000
	s_nop 4
	global_atomic_add v3, v4, v3, s[8:9] offset:1024 sc0
	buffer_inv sc1
	s_sub_u32 s10, 4, s66
	s_add_u32 s11, s10, 1
	s_waitcnt lgkmcnt(0)
	v_readfirstlane_b32 s12, v2
	v_readfirstlane_b32 s13, v1
	s_mul_i32 s14, s12, s11
	s_mul_i32 s15, s13, s11
	s_waitcnt vmcnt(0)
	v_readfirstlane_b32 s16, v3
	s_add_u32 s16, s16, 1
	s_cmp_lg_u32 s16, s14
	s_cbranch_scc1 .Lxb_wait_5
	buffer_wbl2 sc1
	s_waitcnt vmcnt(0)
	v_mov_b32_e32 v3, 1
	v_mov_b32_e32 v4, 0x7f000
	global_atomic_add v3, v4, v3, s[30:31] offset:1024 sc0
	s_waitcnt vmcnt(0)
	v_readfirstlane_b32 s16, v3
	s_add_u32 s16, s16, 1
	s_cmp_lg_u32 s16, s15
	s_cbranch_scc1 .Lxb_wait_5
	v_mov_b32_e32 v3, 1
	v_mov_b32_e32 v4, 0x2400
	global_atomic_add v4, v3, s[6:7]
	v_add_u32_e32 v4, 0x100, v4
	global_atomic_add v4, v3, s[6:7]
	v_add_u32_e32 v4, 0x100, v4
	global_atomic_add v4, v3, s[6:7]
	v_add_u32_e32 v4, 0x100, v4
	global_atomic_add v4, v3, s[6:7]
	v_add_u32_e32 v4, 0x100, v4
	global_atomic_add v4, v3, s[6:7]
	v_add_u32_e32 v4, 0x100, v4
	global_atomic_add v4, v3, s[6:7]
	v_add_u32_e32 v4, 0x100, v4
	global_atomic_add v4, v3, s[6:7]
	v_add_u32_e32 v4, 0x100, v4
	global_atomic_add v4, v3, s[6:7]
	v_add_u32_e32 v4, 0x100, v4
	global_atomic_add v4, v3, s[6:7]
	v_add_u32_e32 v4, 0x100, v4
	global_atomic_add v4, v3, s[6:7]
	v_add_u32_e32 v4, 0x100, v4
	global_atomic_add v4, v3, s[6:7]
	v_add_u32_e32 v4, 0x100, v4
	global_atomic_add v4, v3, s[6:7]
	v_add_u32_e32 v4, 0x100, v4
	global_atomic_add v4, v3, s[6:7]
	v_add_u32_e32 v4, 0x100, v4
	global_atomic_add v4, v3, s[6:7]
	v_add_u32_e32 v4, 0x100, v4
	global_atomic_add v4, v3, s[6:7]
	v_add_u32_e32 v4, 0x100, v4
	global_atomic_add v4, v3, s[6:7]
	v_add_u32_e32 v4, 0x100, v4
	v_mov_b32_e32 v4, 0x7f000
	global_atomic_add v4, v3, s[30:31] offset:1280

.LBB0_1942:
	s_cmpk_eq_i32 s64, 0x200
	s_cbranch_scc0 .Lcv_ret_p4
	s_cmpk_gt_u32 s78, 0xff
	s_cbranch_scc0 .Lcv_ret_p4
	s_mov_b32 s101, 1
	s_movk_i32 s100, 0x11ff
	s_and_b32 s0, s78, 7
	s_lshr_b32 s1, s78, 3
	s_lshl_b32 s0, s0, 5
	s_add_i32 s3, s0, s1
	s_addk_i32 s3, 0xaa0
	s_movk_i32 s2, 0x100
	s_branch .LBB0_1665
.Lcv_ret_p4:
	s_mov_b32 s101, 0
	s_cmp_gt_i32 s67, 9
	s_cbranch_scc0 .LBB0_1992
	s_waitcnt vmcnt(0)
	s_waitcnt vmcnt(63) expcnt(7) lgkmcnt(15)
	s_barrier
	s_mov_b64 s[4:5], exec
	v_readlane_b32 s2, v251, 3
	v_readlane_b32 s3, v251, 4
	s_and_b64 s[2:3], s[4:5], s[2:3]
	s_mov_b64 exec, s[2:3]
	s_cbranch_execz .Lxb_done_9
	v_mov_b32_e32 v0, 0
	s_waitcnt vmcnt(0) expcnt(0) lgkmcnt(0)
	ds_read_b32 v2, v0
	ds_read_b32 v1, v0 offset:4
	v_readlane_b32 s0, v251, 2
	v_readlane_b32 s6, v251, 5
	v_readlane_b32 s7, v251, 6
	s_lshl_b32 s0, s0, 8
	s_add_u32 s8, s6, s0
	s_addc_u32 s9, s7, 0
	v_mov_b32_e32 v3, 1
	v_mov_b32_e32 v4, 0x1000
	s_nop 4
	global_atomic_add v3, v4, v3, s[8:9] offset:1024 sc0
	buffer_inv sc1
	s_sub_u32 s10, 8, s66
	s_add_u32 s11, s10, 1
	s_waitcnt lgkmcnt(0)
	v_readfirstlane_b32 s12, v2
	v_readfirstlane_b32 s13, v1
	s_mul_i32 s14, s12, s11
	s_mul_i32 s15, s13, s11
	s_waitcnt vmcnt(0)
	v_readfirstlane_b32 s16, v3
	s_add_u32 s16, s16, 1
	s_cmp_lg_u32 s16, s14
	s_cbranch_scc1 .Lxb_wait_9
	buffer_wbl2 sc1
	s_waitcnt vmcnt(0)
	v_mov_b32_e32 v3, 1
	v_mov_b32_e32 v4, 0x7f000
	global_atomic_add v3, v4, v3, s[30:31] offset:1024 sc0
	s_waitcnt vmcnt(0)
	v_readfirstlane_b32 s16, v3
	s_add_u32 s16, s16, 1
	s_cmp_lg_u32 s16, s15
	s_cbranch_scc1 .Lxb_wait_9
	v_mov_b32_e32 v3, 1
	v_mov_b32_e32 v4, 0x2400
	global_atomic_add v4, v3, s[6:7]
	v_add_u32_e32 v4, 0x100, v4
	global_atomic_add v4, v3, s[6:7]
	v_add_u32_e32 v4, 0x100, v4
	global_atomic_add v4, v3, s[6:7]
	v_add_u32_e32 v4, 0x100, v4
	global_atomic_add v4, v3, s[6:7]
	v_add_u32_e32 v4, 0x100, v4
	global_atomic_add v4, v3, s[6:7]
	v_add_u32_e32 v4, 0x100, v4
	global_atomic_add v4, v3, s[6:7]
	v_add_u32_e32 v4, 0x100, v4
	global_atomic_add v4, v3, s[6:7]
	v_add_u32_e32 v4, 0x100, v4
	global_atomic_add v4, v3, s[6:7]
	v_add_u32_e32 v4, 0x100, v4
	global_atomic_add v4, v3, s[6:7]
	v_add_u32_e32 v4, 0x100, v4
	global_atomic_add v4, v3, s[6:7]
	v_add_u32_e32 v4, 0x100, v4
	global_atomic_add v4, v3, s[6:7]
	v_add_u32_e32 v4, 0x100, v4
	global_atomic_add v4, v3, s[6:7]
	v_add_u32_e32 v4, 0x100, v4
	global_atomic_add v4, v3, s[6:7]
	v_add_u32_e32 v4, 0x100, v4
	global_atomic_add v4, v3, s[6:7]
	v_add_u32_e32 v4, 0x100, v4
	global_atomic_add v4, v3, s[6:7]
	v_add_u32_e32 v4, 0x100, v4
	global_atomic_add v4, v3, s[6:7]
	v_add_u32_e32 v4, 0x100, v4
	v_mov_b32_e32 v4, 0x7f000
	global_atomic_add v4, v3, s[30:31] offset:1280
